# baseline (speedup 1.0000x reference)
; __device__ __forceinline__ unsigned cvt_pk_bf16(float lo, float hi) { unsigned r; asm volatile("v_cvt_pk_bf16_f32 %0, %1, %2" : "=v"(r) : "v"(lo), "v"(hi)); return r; }
; __device__ __forceinline__ float fq_sum(float x) { float a = x, b = x; pl16(a, b); float y = a + b, c = y; pl32(y, c); return y + c; }
; __device__ __forceinline__ void phase_attn_a(const bf16_t* Qb, const bf16_t* Kb, const bf16_t* Vt, bf16_t* O, const float* lam, const float* subg, const float* qg, const float* kg, float lam_init, LAS unsigned char* lds, int wv) {
;     ...
;         __syncthreads();
;         if (cm == 0) {
; #pragma unroll
;             for (int qb = 0; qb < 2; ++qb) { float ss = 0.f;
; #pragma unroll
;                 for (int db = 0; db < 8; ++db) { const f32x4 o1 = xb[(g * 16 + db * 2 + qb) * 64 + lane]; const f32x4 v = oacc[db][qb] - lam_full * o1; oacc[db][qb] = v;
;                     ss += (v[0] * v[0] + v[1] * v[1]) + (v[2] * v[2] + v[3] * v[3]); }
;                 ss = fq_sum(ss);
;                 const float rinv = rsqrtf(ss * (1.0f / 128.0f) + 1e-5f) * (1.0f - lam_init);
;                 bf16_t* rp = O + (size_t)(b * T + q0 + qb * 16 + cfr) * 1024 + hh * 128 + 8 * cfq;
; #pragma unroll
;                 for (int e = 0; e < 4; ++e) {
;                     const f32x4 g0 = *(const f32x4*)(subg + e * 32 + 8 * cfq), g1 = *(const f32x4*)(subg + e * 32 + 8 * cfq + 4);
;                     const f32x4 v0 = oacc[2 * e][qb] * rinv * g0, v1 = oacc[2 * e + 1][qb] * rinv * g1;
;                     u32x4 w; w.x = cvt_pk_bf16(v0[0], v0[1]); w.y = cvt_pk_bf16(v0[2], v0[3]); w.z = cvt_pk_bf16(v1[0], v1[1]); w.w = cvt_pk_bf16(v1[2], v1[3]); *(u32x4*)(rp + e * 32) = w; } }
.LBB0_1966:
	s_andn2_b64 vcc, exec, s[76:77]
	s_waitcnt lgkmcnt(0)
	s_barrier
	s_cbranch_vccnz .LBB0_1951
	ds_read_b128 v[70:73], v236
	s_xor_b32 s39, s59, 0x80000000
	s_xor_b32 s38, s58, 0x80000000
	v_add_u32_e32 v66, s71, v129
	v_lshlrev_b32_e32 v64, 3, v128
	s_waitcnt lgkmcnt(0)
	v_pk_fma_f32 v[62:63], s[38:39], v[72:73], v[62:63]
	v_pk_fma_f32 v[60:61], s[20:21], v[70:71], v[60:61] neg_lo:[1,0,0] neg_hi:[1,0,0]
	ds_read_b128 v[70:73], v236 offset:2048
	v_mov_b32_e32 v74, v63
	v_ashrrev_i32_e32 v65, 31, v64
	v_ashrrev_i32_e32 v67, 31, v66
	v_lshl_add_u64 v[68:69], v[64:65], 1, s[52:53]
	s_waitcnt lgkmcnt(0)
	v_pk_fma_f32 v[70:71], s[20:21], v[70:71], v[56:57] neg_lo:[1,0,0] neg_hi:[1,0,0]
	v_pk_fma_f32 v[58:59], s[38:39], v[72:73], v[58:59]
	v_mov_b32_e32 v72, v61
	v_mov_b32_e32 v73, v71
	v_mov_b32_e32 v56, v60
	v_mov_b32_e32 v57, v70
	v_pk_mul_f32 v[72:73], v[72:73], v[72:73]
	v_mov_b32_e32 v75, v59
	v_pk_fma_f32 v[56:57], v[56:57], v[56:57], v[72:73]
	v_mov_b32_e32 v72, v62
	v_mov_b32_e32 v73, v58
	v_pk_mul_f32 v[74:75], v[74:75], v[74:75]
	v_lshl_add_u64 v[64:65], v[64:65], 2, s[36:37]
	v_pk_fma_f32 v[72:73], v[72:73], v[72:73], v[74:75]
	s_nop 0
	v_pk_add_f32 v[76:77], v[56:57], v[72:73]
	ds_read_b128 v[72:75], v236 offset:4096
	s_waitcnt lgkmcnt(0)
	v_pk_fma_f32 v[56:57], s[38:39], v[74:75], v[54:55]
	v_pk_fma_f32 v[72:73], s[20:21], v[72:73], v[52:53] neg_lo:[1,0,0] neg_hi:[1,0,0]
	v_pk_mul_f32 v[54:55], v[56:57], v[56:57]
	v_pk_mul_f32 v[52:53], v[72:73], v[72:73]
	s_nop 0
	v_pk_mov_b32 v[74:75], v[52:53], v[54:55] op_sel:[1,0]
	v_mov_b32_e32 v53, v55
	v_pk_add_f32 v[74:75], v[74:75], v[52:53]
	ds_read_b128 v[52:55], v236 offset:6144
	s_waitcnt lgkmcnt(0)
	v_pk_fma_f32 v[78:79], s[38:39], v[54:55], v[42:43]
	v_pk_fma_f32 v[80:81], s[20:21], v[52:53], v[40:41] neg_lo:[1,0,0] neg_hi:[1,0,0]
	ds_read_b128 v[40:43], v236 offset:8192
	s_waitcnt lgkmcnt(0)
	v_pk_fma_f32 v[54:55], s[20:21], v[40:41], v[44:45] neg_lo:[1,0,0] neg_hi:[1,0,0]
	v_pk_fma_f32 v[52:53], s[38:39], v[42:43], v[46:47]
	v_mul_f32_e32 v42, v54, v54
	v_pk_add_f32 v[40:41], v[76:77], v[76:77] op_sel:[0,1] op_sel_hi:[1,0]
	v_mul_f32_e32 v44, v55, v55
	v_mov_b32_e32 v41, v42
	v_pk_add_f32 v[42:43], v[74:75], v[74:75] op_sel:[0,1] op_sel_hi:[1,0]
	v_mul_f32_e32 v45, v52, v52
	v_mov_b32_e32 v43, v44
	v_pk_add_f32 v[40:41], v[40:41], v[42:43]
	v_mul_f32_e32 v42, v81, v81
	v_pk_fma_f32 v[42:43], v[80:81], v[80:81], v[42:43] op_sel_hi:[1,1,0]
	v_mul_f32_e32 v44, v79, v79
	v_mul_f32_e32 v46, v53, v53
	v_mov_b32_e32 v43, v45
	v_pk_fma_f32 v[44:45], v[78:79], v[78:79], v[44:45] op_sel_hi:[1,1,0]
	s_nop 0
	v_mov_b32_e32 v45, v46
	v_pk_add_f32 v[42:43], v[42:43], v[44:45]
	s_nop 0
	v_pk_add_f32 v[82:83], v[40:41], v[42:43]
	ds_read_b128 v[40:43], v236 offset:10240
	s_waitcnt lgkmcnt(0)
	v_pk_fma_f32 v[74:75], s[38:39], v[42:43], v[38:39]
	v_pk_fma_f32 v[76:77], s[20:21], v[40:41], v[36:37] neg_lo:[1,0,0] neg_hi:[1,0,0]
	v_pk_mul_f32 v[38:39], v[74:75], v[74:75]
	v_pk_mul_f32 v[36:37], v[76:77], v[76:77]
	s_nop 0
	v_pk_mov_b32 v[40:41], v[36:37], v[38:39] op_sel:[1,0]
	v_mov_b32_e32 v37, v39
	v_pk_add_f32 v[84:85], v[40:41], v[36:37]
	ds_read_b128 v[36:39], v236 offset:12288
	s_waitcnt lgkmcnt(0)
	v_pk_fma_f32 v[42:43], s[38:39], v[38:39], v[34:35]
	v_pk_fma_f32 v[46:47], s[20:21], v[36:37], v[32:33] neg_lo:[1,0,0] neg_hi:[1,0,0]
	ds_read_b128 v[32:35], v236 offset:14336
	s_waitcnt lgkmcnt(0)
	v_pk_fma_f32 v[44:45], s[20:21], v[32:33], v[48:49] neg_lo:[1,0,0] neg_hi:[1,0,0]
	v_pk_fma_f32 v[40:41], s[38:39], v[34:35], v[50:51]
	v_mul_f32_e32 v34, v44, v44
	v_pk_add_f32 v[32:33], v[82:83], v[82:83] op_sel:[0,1] op_sel_hi:[1,0]
	v_mul_f32_e32 v36, v45, v45
	v_mov_b32_e32 v33, v34
	v_pk_add_f32 v[34:35], v[84:85], v[84:85] op_sel:[0,1] op_sel_hi:[1,0]
	v_mul_f32_e32 v37, v40, v40
	v_mov_b32_e32 v35, v36
	v_pk_add_f32 v[32:33], v[32:33], v[34:35]
	v_mul_f32_e32 v34, v47, v47
	v_pk_fma_f32 v[34:35], v[46:47], v[46:47], v[34:35] op_sel_hi:[1,1,0]
	v_mul_f32_e32 v36, v43, v43
	v_mul_f32_e32 v38, v41, v41
	v_mov_b32_e32 v35, v37
	v_pk_fma_f32 v[36:37], v[42:43], v[42:43], v[36:37] op_sel_hi:[1,1,0]
	v_mov_b32_e32 v51, 0x3727c5ac
	v_mov_b32_e32 v37, v38
	v_pk_add_f32 v[34:35], v[34:35], v[36:37]
	s_nop 0
	v_pk_add_f32 v[32:33], v[32:33], v[34:35]
	s_nop 0
	v_add_f32_e32 v32, v32, v33
	v_mov_b32_e32 v33, v32
	s_nop 1
	v_permlane16_swap_b32 v33, v32
	s_nop 0
	v_add_f32_e32 v32, v33, v32
	v_mov_b32_e32 v33, v32
	s_nop 1
	v_permlane32_swap_b32 v33, v32
	s_nop 0
	v_add_f32_e32 v32, v33, v32
	v_fmamk_f32 v32, v32, 0x3c000000, v51
	v_cmp_gt_f32_e32 vcc, s2, v32
	v_mul_f32_e32 v33, 0x4b800000, v32
	s_nop 0
	v_cndmask_b32_e32 v32, v32, v33, vcc
	v_rsq_f32_e32 v32, v32
	s_nop 0
	v_mul_f32_e32 v33, 0x45800000, v32
	v_cndmask_b32_e32 v32, v32, v33, vcc
	v_mul_f32_e32 v50, v234, v32
	v_lshlrev_b64 v[32:33], 11, v[66:67]
	v_lshl_add_u64 v[48:49], v[68:69], 0, v[32:33]
	global_load_dwordx4 v[132:135], v[64:65], off
	global_load_dwordx4 v[136:139], v[64:65], off offset:16
	global_load_dwordx4 v[140:143], v[64:65], off offset:128
	global_load_dwordx4 v[144:147], v[64:65], off offset:144
	global_load_dwordx4 v[148:151], v[64:65], off offset:256
	global_load_dwordx4 v[152:155], v[64:65], off offset:272
	global_load_dwordx4 v[156:159], v[64:65], off offset:384
	global_load_dwordx4 v[160:163], v[64:65], off offset:400
	v_pk_mul_f32 v[60:61], v[60:61], v[50:51] op_sel_hi:[1,0]
	v_pk_mul_f32 v[58:59], v[58:59], v[50:51] op_sel_hi:[1,0]
	v_pk_mul_f32 v[62:63], v[62:63], v[50:51] op_sel_hi:[1,0]
	v_pk_mul_f32 v[56:57], v[56:57], v[50:51] op_sel_hi:[1,0]
	v_pk_mul_f32 v[54:55], v[54:55], v[50:51] op_sel_hi:[1,0]
	v_pk_mul_f32 v[52:53], v[52:53], v[50:51] op_sel_hi:[1,0]
	v_pk_mul_f32 v[42:43], v[42:43], v[50:51] op_sel_hi:[1,0]
	v_pk_mul_f32 v[40:41], v[40:41], v[50:51] op_sel_hi:[1,0]
	v_pk_mul_f32 v[46:47], v[46:47], v[50:51] op_sel_hi:[1,0]
	s_waitcnt vmcnt(0)
; __device__ __forceinline__ unsigned cvt_pk_bf16(float lo, float hi) { unsigned r; asm volatile("v_cvt_pk_bf16_f32 %0, %1, %2" : "=v"(r) : "v"(lo), "v"(hi)); return r; }
; __device__ __forceinline__ float fq_sum(float x) { float a = x, b = x; pl16(a, b); float y = a + b, c = y; pl32(y, c); return y + c; }
; __device__ __forceinline__ void phase_attn_a(const bf16_t* Qb, const bf16_t* Kb, const bf16_t* Vt, bf16_t* O, const float* lam, const float* subg, const float* qg, const float* kg, float lam_init, LAS unsigned char* lds, int wv) {
;     ...
;             for (int qb = 0; qb < 2; ++qb) { float ss = 0.f;
; #pragma unroll
;                 for (int db = 0; db < 8; ++db) { const f32x4 o1 = xb[(g * 16 + db * 2 + qb) * 64 + lane]; const f32x4 v = oacc[db][qb] - lam_full * o1; oacc[db][qb] = v;
;                     ss += (v[0] * v[0] + v[1] * v[1]) + (v[2] * v[2] + v[3] * v[3]); }
;                 ss = fq_sum(ss);
;                 const float rinv = rsqrtf(ss * (1.0f / 128.0f) + 1e-5f) * (1.0f - lam_init);
;                 bf16_t* rp = O + (size_t)(b * T + q0 + qb * 16 + cfr) * 1024 + hh * 128 + 8 * cfq;
; #pragma unroll
;                 for (int e = 0; e < 4; ++e) {
;                     const f32x4 g0 = *(const f32x4*)(subg + e * 32 + 8 * cfq), g1 = *(const f32x4*)(subg + e * 32 + 8 * cfq + 4);
;                     const f32x4 v0 = oacc[2 * e][qb] * rinv * g0, v1 = oacc[2 * e + 1][qb] * rinv * g1;
;                     u32x4 w; w.x = cvt_pk_bf16(v0[0], v0[1]); w.y = cvt_pk_bf16(v0[2], v0[3]); w.z = cvt_pk_bf16(v1[0], v1[1]); w.w = cvt_pk_bf16(v1[2], v1[3]); *(u32x4*)(rp + e * 32) = w; } }
	v_pk_mul_f32 v[58:59], v[138:139], v[58:59]
	s_waitcnt vmcnt(0)
	v_pk_mul_f32 v[36:37], v[132:133], v[60:61]
	v_pk_mul_f32 v[60:61], v[70:71], v[50:51] op_sel_hi:[1,0]
	v_pk_mul_f32 v[38:39], v[134:135], v[62:63]
	v_pk_mul_f32 v[34:35], v[136:137], v[60:61]
	v_cvt_pk_bf16_f32 v32, v36, v37
	v_cvt_pk_bf16_f32 v33, v38, v39
	s_nop 0
	v_cvt_pk_bf16_f32 v34, v34, v35
	v_cvt_pk_bf16_f32 v35, v58, v59
	global_store_dwordx4 v[48:49], v[32:35], off
	s_nop 1
	v_pk_mul_f32 v[58:59], v[72:73], v[50:51] op_sel_hi:[1,0]
	v_pk_mul_f32 v[38:39], v[142:143], v[56:57]
	v_pk_mul_f32 v[36:37], v[140:141], v[58:59]
	v_pk_mul_f32 v[56:57], v[80:81], v[50:51] op_sel_hi:[1,0]
	v_pk_mul_f32 v[58:59], v[78:79], v[50:51] op_sel_hi:[1,0]
	s_nop 0
	v_pk_mul_f32 v[58:59], v[146:147], v[58:59]
	v_pk_mul_f32 v[34:35], v[144:145], v[56:57]
	v_cvt_pk_bf16_f32 v32, v36, v37
	v_cvt_pk_bf16_f32 v33, v38, v39
	s_nop 0
	v_cvt_pk_bf16_f32 v34, v34, v35
	v_cvt_pk_bf16_f32 v35, v58, v59
	global_store_dwordx4 v[48:49], v[32:35], off offset:64
	s_nop 1
	v_pk_mul_f32 v[38:39], v[52:53], v[150:151]
	v_pk_mul_f32 v[36:37], v[54:55], v[148:149]
	v_pk_mul_f32 v[52:53], v[76:77], v[50:51] op_sel_hi:[1,0]
	v_pk_mul_f32 v[54:55], v[74:75], v[50:51] op_sel_hi:[1,0]
	s_nop 0
	v_pk_mul_f32 v[54:55], v[54:55], v[154:155]
	v_pk_mul_f32 v[34:35], v[52:53], v[152:153]
	v_cvt_pk_bf16_f32 v32, v36, v37
	v_cvt_pk_bf16_f32 v33, v38, v39
	s_nop 0
	v_cvt_pk_bf16_f32 v34, v34, v35
	v_cvt_pk_bf16_f32 v35, v54, v55
	global_store_dwordx4 v[48:49], v[32:35], off offset:128
	s_nop 1
	v_pk_mul_f32 v[40:41], v[40:41], v[162:163]
	v_pk_mul_f32 v[38:39], v[42:43], v[158:159]
	v_pk_mul_f32 v[42:43], v[44:45], v[50:51] op_sel_hi:[1,0]
	v_pk_mul_f32 v[36:37], v[46:47], v[156:157]
	v_pk_mul_f32 v[34:35], v[42:43], v[160:161]
	v_cvt_pk_bf16_f32 v32, v36, v37
	v_cvt_pk_bf16_f32 v33, v38, v39
	s_nop 0
	v_cvt_pk_bf16_f32 v34, v34, v35
	v_cvt_pk_bf16_f32 v35, v40, v41
	global_store_dwordx4 v[48:49], v[32:35], off offset:192
	s_nop 1
	ds_read_b128 v[32:35], v236 offset:1024
	s_waitcnt lgkmcnt(0)
	v_pk_fma_f32 v[40:41], s[38:39], v[34:35], v[22:23]
	v_pk_fma_f32 v[42:43], s[20:21], v[32:33], v[20:21] neg_lo:[1,0,0] neg_hi:[1,0,0]
	ds_read_b128 v[20:23], v236 offset:3072
	s_waitcnt lgkmcnt(0)
	v_pk_fma_f32 v[38:39], s[20:21], v[20:21], v[28:29] neg_lo:[1,0,0] neg_hi:[1,0,0]
	v_pk_fma_f32 v[36:37], s[38:39], v[22:23], v[30:31]
	v_mov_b32_e32 v22, v43
	v_mov_b32_e32 v23, v39
	v_mov_b32_e32 v20, v42
	v_mov_b32_e32 v21, v38
	v_pk_mul_f32 v[22:23], v[22:23], v[22:23]
	v_mov_b32_e32 v28, v41
	v_mov_b32_e32 v29, v37
	v_pk_fma_f32 v[20:21], v[20:21], v[20:21], v[22:23]
	v_mov_b32_e32 v22, v40
	v_mov_b32_e32 v23, v36
	v_pk_mul_f32 v[28:29], v[28:29], v[28:29]
	s_nop 0
	v_pk_fma_f32 v[22:23], v[22:23], v[22:23], v[28:29]
	s_nop 0
	v_pk_add_f32 v[44:45], v[20:21], v[22:23]
	ds_read_b128 v[20:23], v236 offset:5120
	s_waitcnt lgkmcnt(0)
	v_pk_fma_f32 v[32:33], s[38:39], v[22:23], v[18:19]
	v_pk_fma_f32 v[34:35], s[20:21], v[20:21], v[16:17] neg_lo:[1,0,0] neg_hi:[1,0,0]
	v_pk_mul_f32 v[18:19], v[32:33], v[32:33]
	v_pk_mul_f32 v[16:17], v[34:35], v[34:35]
	s_nop 0
	v_pk_mov_b32 v[20:21], v[16:17], v[18:19] op_sel:[1,0]
	v_mov_b32_e32 v17, v19
	v_pk_add_f32 v[22:23], v[20:21], v[16:17]
	ds_read_b128 v[16:19], v236 offset:7168
	s_waitcnt lgkmcnt(0)
	v_pk_fma_f32 v[28:29], s[38:39], v[18:19], v[14:15]
	v_pk_fma_f32 v[30:31], s[20:21], v[16:17], v[12:13] neg_lo:[1,0,0] neg_hi:[1,0,0]
	ds_read_b128 v[12:15], v236 offset:9216
	s_waitcnt lgkmcnt(0)
	v_pk_fma_f32 v[20:21], s[20:21], v[12:13], v[24:25] neg_lo:[1,0,0] neg_hi:[1,0,0]
	v_pk_fma_f32 v[18:19], s[38:39], v[14:15], v[26:27]
	v_mul_f32_e32 v14, v20, v20
	v_pk_add_f32 v[12:13], v[44:45], v[44:45] op_sel:[0,1] op_sel_hi:[1,0]
	v_mul_f32_e32 v16, v21, v21
	v_mov_b32_e32 v13, v14
	v_pk_add_f32 v[14:15], v[22:23], v[22:23] op_sel:[0,1] op_sel_hi:[1,0]
	v_mul_f32_e32 v17, v18, v18
	v_mov_b32_e32 v15, v16
	v_pk_add_f32 v[12:13], v[12:13], v[14:15]
	v_mul_f32_e32 v14, v31, v31
	v_pk_fma_f32 v[14:15], v[30:31], v[30:31], v[14:15] op_sel_hi:[1,1,0]
	v_mul_f32_e32 v16, v29, v29
	v_mul_f32_e32 v24, v19, v19
	v_mov_b32_e32 v15, v17
	v_pk_fma_f32 v[16:17], v[28:29], v[28:29], v[16:17] op_sel_hi:[1,1,0]
	s_nop 0
	v_mov_b32_e32 v17, v24
	v_pk_add_f32 v[14:15], v[14:15], v[16:17]
	s_nop 0
	v_pk_add_f32 v[16:17], v[12:13], v[14:15]
	ds_read_b128 v[12:15], v236 offset:11264
	s_waitcnt lgkmcnt(0)
; __device__ __forceinline__ unsigned cvt_pk_bf16(float lo, float hi) { unsigned r; asm volatile("v_cvt_pk_bf16_f32 %0, %1, %2" : "=v"(r) : "v"(lo), "v"(hi)); return r; }
; __device__ __forceinline__ float fq_sum(float x) { float a = x, b = x; pl16(a, b); float y = a + b, c = y; pl32(y, c); return y + c; }
; __device__ __forceinline__ void phase_attn_a(const bf16_t* Qb, const bf16_t* Kb, const bf16_t* Vt, bf16_t* O, const float* lam, const float* subg, const float* qg, const float* kg, float lam_init, LAS unsigned char* lds, int wv) {
;     ...
;             for (int qb = 0; qb < 2; ++qb) { float ss = 0.f;
; #pragma unroll
;                 for (int db = 0; db < 8; ++db) { const f32x4 o1 = xb[(g * 16 + db * 2 + qb) * 64 + lane]; const f32x4 v = oacc[db][qb] - lam_full * o1; oacc[db][qb] = v;
;                     ss += (v[0] * v[0] + v[1] * v[1]) + (v[2] * v[2] + v[3] * v[3]); }
;                 ss = fq_sum(ss);
;                 const float rinv = rsqrtf(ss * (1.0f / 128.0f) + 1e-5f) * (1.0f - lam_init);
;                 bf16_t* rp = O + (size_t)(b * T + q0 + qb * 16 + cfr) * 1024 + hh * 128 + 8 * cfq;
; #pragma unroll
;                 for (int e = 0; e < 4; ++e) {
;                     const f32x4 g0 = *(const f32x4*)(subg + e * 32 + 8 * cfq), g1 = *(const f32x4*)(subg + e * 32 + 8 * cfq + 4);
;                     const f32x4 v0 = oacc[2 * e][qb] * rinv * g0, v1 = oacc[2 * e + 1][qb] * rinv * g1;
;                     u32x4 w; w.x = cvt_pk_bf16(v0[0], v0[1]); w.y = cvt_pk_bf16(v0[2], v0[3]); w.z = cvt_pk_bf16(v1[0], v1[1]); w.w = cvt_pk_bf16(v1[2], v1[3]); *(u32x4*)(rp + e * 32) = w; } }
	v_pk_fma_f32 v[22:23], s[38:39], v[14:15], v[6:7]
	v_pk_fma_f32 v[24:25], s[20:21], v[12:13], v[4:5] neg_lo:[1,0,0] neg_hi:[1,0,0]
	v_pk_mul_f32 v[6:7], v[22:23], v[22:23]
	v_pk_mul_f32 v[4:5], v[24:25], v[24:25]
	s_nop 0
	v_pk_mov_b32 v[12:13], v[4:5], v[6:7] op_sel:[1,0]
	v_mov_b32_e32 v5, v7
	v_pk_add_f32 v[26:27], v[12:13], v[4:5]
	ds_read_b128 v[4:7], v236 offset:13312
	s_waitcnt lgkmcnt(0)
	v_pk_fma_f32 v[12:13], s[38:39], v[6:7], v[2:3]
	v_pk_fma_f32 v[14:15], s[20:21], v[4:5], v[0:1] neg_lo:[1,0,0] neg_hi:[1,0,0]
	ds_read_b128 v[0:3], v236 offset:15360
	s_waitcnt lgkmcnt(0)
	v_pk_fma_f32 v[8:9], s[20:21], v[0:1], v[8:9] neg_lo:[1,0,0] neg_hi:[1,0,0]
	v_pk_fma_f32 v[10:11], s[38:39], v[2:3], v[10:11]
	v_mul_f32_e32 v2, v8, v8
	v_pk_add_f32 v[0:1], v[16:17], v[16:17] op_sel:[0,1] op_sel_hi:[1,0]
	v_mul_f32_e32 v4, v9, v9
	v_mov_b32_e32 v1, v2
	v_pk_add_f32 v[2:3], v[26:27], v[26:27] op_sel:[0,1] op_sel_hi:[1,0]
	v_mul_f32_e32 v5, v10, v10
	v_mov_b32_e32 v3, v4
	v_pk_add_f32 v[0:1], v[0:1], v[2:3]
	v_mul_f32_e32 v2, v15, v15
	v_pk_fma_f32 v[2:3], v[14:15], v[14:15], v[2:3] op_sel_hi:[1,1,0]
	v_mul_f32_e32 v4, v13, v13
	v_mul_f32_e32 v6, v11, v11
	v_mov_b32_e32 v3, v5
	v_pk_fma_f32 v[4:5], v[12:13], v[12:13], v[4:5] op_sel_hi:[1,1,0]
	s_nop 0
	v_mov_b32_e32 v5, v6
	v_pk_add_f32 v[2:3], v[2:3], v[4:5]
	s_nop 0
	v_pk_add_f32 v[0:1], v[0:1], v[2:3]
	s_nop 0
	v_add_f32_e32 v0, v0, v1
	v_mov_b32_e32 v1, v0
	s_nop 1
	v_permlane16_swap_b32 v1, v0
	s_nop 0
	v_add_f32_e32 v0, v1, v0
	v_mov_b32_e32 v1, v0
	s_nop 1
	v_permlane32_swap_b32 v1, v0
	s_nop 0
	v_add_f32_e32 v0, v1, v0
	v_fmamk_f32 v0, v0, 0x3c000000, v51
	v_cmp_gt_f32_e32 vcc, s2, v0
	v_mul_f32_e32 v1, 0x4b800000, v0
	s_nop 0
	v_cndmask_b32_e32 v0, v0, v1, vcc
	v_rsq_f32_e32 v0, v0
	s_nop 0
	v_mul_f32_e32 v1, 0x45800000, v0
	v_cndmask_b32_e32 v0, v0, v1, vcc
	v_mul_f32_e32 v16, v234, v0
	v_add_u32_e32 v0, 16, v66
	v_ashrrev_i32_e32 v1, 31, v0
	v_lshlrev_b64 v[0:1], 11, v[0:1]
	v_lshl_add_u64 v[26:27], v[68:69], 0, v[0:1]
	v_pk_mul_f32 v[38:39], v[38:39], v[16:17] op_sel_hi:[1,0]
	v_pk_mul_f32 v[36:37], v[36:37], v[16:17] op_sel_hi:[1,0]
	v_pk_mul_f32 v[42:43], v[42:43], v[16:17] op_sel_hi:[1,0]
	v_pk_mul_f32 v[40:41], v[40:41], v[16:17] op_sel_hi:[1,0]
	v_pk_mul_f32 v[30:31], v[30:31], v[16:17] op_sel_hi:[1,0]
	v_pk_mul_f32 v[28:29], v[28:29], v[16:17] op_sel_hi:[1,0]
	v_pk_mul_f32 v[34:35], v[34:35], v[16:17] op_sel_hi:[1,0]
	v_pk_mul_f32 v[32:33], v[32:33], v[16:17] op_sel_hi:[1,0]
	v_pk_mul_f32 v[20:21], v[20:21], v[16:17] op_sel_hi:[1,0]
	v_pk_mul_f32 v[18:19], v[18:19], v[16:17] op_sel_hi:[1,0]
	v_pk_mul_f32 v[8:9], v[8:9], v[16:17] op_sel_hi:[1,0]
	v_pk_mul_f32 v[10:11], v[10:11], v[16:17] op_sel_hi:[1,0]
	v_pk_mul_f32 v[14:15], v[14:15], v[16:17] op_sel_hi:[1,0]
	v_pk_mul_f32 v[12:13], v[12:13], v[16:17] op_sel_hi:[1,0]
	v_pk_mul_f32 v[36:37], v[138:139], v[36:37]
	v_pk_mul_f32 v[2:3], v[136:137], v[38:39]
	v_pk_mul_f32 v[6:7], v[134:135], v[40:41]
	v_pk_mul_f32 v[4:5], v[132:133], v[42:43]
	s_nop 0
	v_cvt_pk_bf16_f32 v0, v4, v5
	v_cvt_pk_bf16_f32 v1, v6, v7
	v_cvt_pk_bf16_f32 v2, v2, v3
	v_cvt_pk_bf16_f32 v3, v36, v37
	global_store_dwordx4 v[26:27], v[0:3], off
	s_nop 1
	v_pk_mul_f32 v[28:29], v[146:147], v[28:29]
	v_pk_mul_f32 v[2:3], v[144:145], v[30:31]
	v_pk_mul_f32 v[6:7], v[142:143], v[32:33]
	v_pk_mul_f32 v[4:5], v[140:141], v[34:35]
	s_nop 0
	v_cvt_pk_bf16_f32 v0, v4, v5
	v_cvt_pk_bf16_f32 v1, v6, v7
	v_cvt_pk_bf16_f32 v2, v2, v3
	v_cvt_pk_bf16_f32 v3, v28, v29
	global_store_dwordx4 v[26:27], v[0:3], off offset:64
	s_nop 1
	v_pk_mul_f32 v[6:7], v[18:19], v[150:151]
	v_pk_mul_f32 v[4:5], v[20:21], v[148:149]
	v_pk_mul_f32 v[18:19], v[24:25], v[16:17] op_sel_hi:[1,0]
	v_pk_mul_f32 v[20:21], v[22:23], v[16:17] op_sel_hi:[1,0]
	s_nop 0
	v_pk_mul_f32 v[20:21], v[20:21], v[154:155]
	v_pk_mul_f32 v[2:3], v[18:19], v[152:153]
	v_cvt_pk_bf16_f32 v0, v4, v5
	v_cvt_pk_bf16_f32 v1, v6, v7
	s_nop 0
	v_cvt_pk_bf16_f32 v2, v2, v3
	v_cvt_pk_bf16_f32 v3, v20, v21
	global_store_dwordx4 v[26:27], v[0:3], off offset:128
	s_nop 1
	v_pk_mul_f32 v[10:11], v[10:11], v[162:163]
	v_pk_mul_f32 v[2:3], v[8:9], v[160:161]
	v_pk_mul_f32 v[6:7], v[12:13], v[158:159]
	v_pk_mul_f32 v[4:5], v[14:15], v[156:157]
	s_nop 0
	v_cvt_pk_bf16_f32 v0, v4, v5
	v_cvt_pk_bf16_f32 v1, v6, v7
	v_cvt_pk_bf16_f32 v2, v2, v3
	v_cvt_pk_bf16_f32 v3, v10, v11
	global_store_dwordx4 v[26:27], v[0:3], off offset:192
	s_nop 1
	s_branch .LBB0_1951
